# post phase: loop-invariant LayerNorm gamma/beta loads hoisted out of the item loop (7 instead of 11 VMEM ops per item)
# speedup vs baseline: 1.0077x; 1.0077x over previous
.LBB0_963:
	s_or_b64 exec, exec, s[68:69]
	s_mov_b32 s0, s45
	s_waitcnt lgkmcnt(0)
	s_barrier
	s_add_i32 s0, s0, 0x200e8
	v_mov_b32_e32 v0, s0
	ds_read_b64 v[2:3], v0
	s_mov_b32 s2, 0
	s_add_i32 s2, s2, 0x200e8
	v_mov_b32_e32 v0, s2
	s_mov_b32 s2, 0
	s_waitcnt lgkmcnt(0)
	v_readfirstlane_b32 s1, v3
	v_readfirstlane_b32 s0, v2
	ds_read_b64 v[2:3], v0
	s_add_i32 s2, s2, 0x200e8
	v_mov_b32_e32 v0, s2
	s_mov_b32 s2, 0
	ds_read_b64 v[4:5], v0
	s_add_i32 s2, s2, 0x200e8
	v_mov_b32_e32 v0, s2
	s_mov_b32 s2, 0
	ds_read_b64 v[6:7], v0
	s_add_i32 s2, s2, 0x200e8
	v_mov_b32_e32 v0, s2
	s_mov_b32 s2, 0
	s_waitcnt lgkmcnt(0)
	v_readfirstlane_b32 s5, v3
	v_readfirstlane_b32 s4, v2
	ds_read_b64 v[2:3], v0
	s_add_i32 s2, s2, 0x20078
	v_mov_b32_e32 v0, s2
	s_mov_b32 s2, 0
	v_readfirstlane_b32 s7, v5
	v_readfirstlane_b32 s6, v4
	ds_read_b64 v[4:5], v0
	s_add_i32 s2, s2, 0x20080
	v_mov_b32_e32 v0, s2
	v_readfirstlane_b32 s9, v7
	v_readfirstlane_b32 s8, v6
	ds_read_b64 v[6:7], v0
	v_readlane_b32 s14, v252, 0
	v_mov_b32_e32 v0, v200
	s_mov_b32 s2, 0x200000
	v_lshl_add_u32 v40, s14, 9, v0
	s_waitcnt lgkmcnt(0)
	v_readfirstlane_b32 s11, v3
	v_readfirstlane_b32 s10, v2
	v_readfirstlane_b32 s13, v5
	v_readfirstlane_b32 s12, v4
	v_readfirstlane_b32 s15, v7
	v_readfirstlane_b32 s16, v6
	v_cmp_gt_i32_e32 vcc, s2, v40
	s_and_saveexec_b64 s[2:3], vcc
	s_cbranch_execz .LBB0_966
	s_add_u32 s4, s4, 0x4bf0000
	s_addc_u32 s5, s5, 0
	s_add_u32 s6, s6, 0x2bf0000
	s_addc_u32 s7, s7, 0
	s_add_u32 s8, s8, 0x210000
	s_addc_u32 s9, s9, 0
	s_add_u32 s10, s10, 0x110000
	s_addc_u32 s11, s11, 0
	s_lshl_b64 s[18:19], s[70:71], 2
	s_add_u32 s12, s12, s18
	s_addc_u32 s13, s13, s19
	s_add_u32 s18, s16, s18
	v_lshlrev_b32_e32 v0, 3, v0
	s_addc_u32 s19, s15, s19
	v_lshl_add_u32 v41, s14, 12, v0
	s_mov_b64 s[20:21], 0
	v_mov_b32_e32 v61, 0
	v_and_b32_e32 v114, 0x1f8, v41
	v_lshlrev_b32_e32 v114, 2, v114
	v_mov_b32_e32 v115, 0
	v_lshl_add_u64 v[132:133], s[12:13], 0, v[114:115]
	v_lshl_add_u64 v[114:115], s[18:19], 0, v[114:115]
	global_load_dwordx4 v[116:119], v[132:133], off
	global_load_dwordx4 v[120:123], v[132:133], off offset:16
	global_load_dwordx4 v[124:127], v[114:115], off
	global_load_dwordx4 v[128:131], v[114:115], off offset:16
.LBB0_965:
	v_ashrrev_i32_e32 v2, 6, v40
	v_and_b32_e32 v10, 0x1f8, v41
	v_mov_b64_e32 v[4:5], s[0:1]
	v_ashrrev_i32_e32 v3, 31, v2
	v_mad_i64_i32 v[4:5], s[14:15], v2, s95, v[4:5]
	v_lshlrev_b32_e32 v0, 1, v10
	v_bfe_u32 v11, v41, 6, 3
	v_lshl_add_u64 v[4:5], v[4:5], 0, v[0:1]
	v_lshlrev_b64 v[6:7], 10, v[2:3]
	v_lshlrev_b64 v[2:3], 3, v[2:3]
	v_add_co_u32_e32 v38, vcc, 0x8bf0000, v4
	v_lshl_add_u64 v[8:9], s[4:5], 0, v[6:7]
	v_or_b32_e32 v2, v2, v11
	v_addc_co_u32_e32 v39, vcc, 0, v5, vcc
	v_lshl_add_u64 v[4:5], v[8:9], 0, v[0:1]
	v_lshlrev_b64 v[8:9], 5, v[2:3]
	v_lshl_add_u64 v[6:7], s[6:7], 0, v[6:7]
	v_lshl_add_u64 v[42:43], v[2:3], 2, s[10:11]
	v_lshl_add_u64 v[2:3], s[8:9], 0, v[8:9]
	v_lshl_add_u64 v[6:7], v[6:7], 0, v[0:1]
	flat_load_dwordx4 v[30:33], v[38:39] offset:1024
	flat_load_dwordx4 v[22:25], v[4:5]
	flat_load_dwordx4 v[18:21], v[6:7]
	flat_load_dwordx4 v[34:37], v[2:3]
	flat_load_dwordx4 v[26:29], v[2:3] offset:16
	flat_load_dword v0, v[42:43]
	s_mov_b32 s22, 0x3c800000
	v_add_u32_e32 v40, s38, v40
	s_mov_b32 s14, 0x1fffff
	v_cmp_lt_i32_e32 vcc, s14, v40
	s_or_b64 s[20:21], vcc, s[20:21]
	v_add_u32_e32 v41, s54, v41
	v_ashrrev_i32_e32 v62, 6, v40
	v_and_b32_e32 v70, 0x1f8, v41
	v_mov_b64_e32 v[64:65], s[0:1]
	v_ashrrev_i32_e32 v63, 31, v62
	v_mad_i64_i32 v[64:65], s[14:15], v62, s95, v[64:65]
	v_lshlrev_b32_e32 v60, 1, v70
	v_bfe_u32 v71, v41, 6, 3
	v_lshl_add_u64 v[64:65], v[64:65], 0, v[60:61]
	v_lshlrev_b64 v[66:67], 10, v[62:63]
	v_lshlrev_b64 v[62:63], 3, v[62:63]
	v_add_co_u32_e32 v98, vcc, 0x8bf0000, v64
	v_lshl_add_u64 v[68:69], s[4:5], 0, v[66:67]
	v_or_b32_e32 v62, v62, v71
	v_addc_co_u32_e32 v99, vcc, 0, v65, vcc
	v_lshl_add_u64 v[64:65], v[68:69], 0, v[60:61]
	v_lshlrev_b64 v[68:69], 5, v[62:63]
	v_lshl_add_u64 v[66:67], s[6:7], 0, v[66:67]
	v_lshl_add_u64 v[102:103], v[62:63], 2, s[10:11]
	v_lshl_add_u64 v[62:63], s[8:9], 0, v[68:69]
	v_lshl_add_u64 v[66:67], v[66:67], 0, v[60:61]
	flat_load_dwordx4 v[90:93], v[98:99] offset:1024
	flat_load_dwordx4 v[82:85], v[64:65]
	flat_load_dwordx4 v[78:81], v[66:67]
	flat_load_dwordx4 v[94:97], v[62:63]
	flat_load_dwordx4 v[86:89], v[62:63] offset:16
	flat_load_dword v60, v[102:103]
	s_mov_b32 s22, 0x3c800000
	v_add_u32_e32 v40, s38, v40
	s_mov_b32 s14, 0x1fffff
	v_cmp_lt_i32_e32 vcc, s14, v40
	s_or_b64 s[20:21], vcc, s[20:21]
	v_add_u32_e32 v41, s54, v41
	s_waitcnt vmcnt(0) lgkmcnt(0)
	v_lshlrev_b32_e32 v42, 16, v30
	v_and_b32_e32 v43, 0xffff0000, v30
	v_pk_add_f32 v[34:35], v[34:35], v[36:37]
	v_lshlrev_b32_e32 v30, 16, v31
	v_pk_add_f32 v[26:27], v[34:35], v[26:27]
	v_and_b32_e32 v31, 0xffff0000, v31
	v_pk_add_f32 v[26:27], v[28:29], v[26:27]
	v_lshlrev_b32_e32 v48, 16, v32
	v_pk_mul_f32 v[26:27], v[26:27], s[22:23] op_sel_hi:[1,0]
	v_and_b32_e32 v49, 0xffff0000, v32
	v_lshlrev_b32_e32 v32, 16, v33
	v_and_b32_e32 v33, 0xffff0000, v33
	v_fma_f32 v36, -v26, v26, v27
	v_pk_add_f32 v[28:29], v[42:43], v[26:27] op_sel_hi:[1,0] neg_lo:[0,1] neg_hi:[0,1]
	v_pk_add_f32 v[30:31], v[30:31], v[26:27] op_sel_hi:[1,0] neg_lo:[0,1] neg_hi:[0,1]
	v_pk_add_f32 v[34:35], v[48:49], v[26:27] op_sel_hi:[1,0] neg_lo:[0,1] neg_hi:[0,1]
	v_pk_add_f32 v[26:27], v[32:33], v[26:27] op_sel_hi:[1,0] neg_lo:[0,1] neg_hi:[0,1]
	v_max_f32_e32 v32, 0, v36
	v_add_f32_e32 v32, 0x3a27c5ac, v32
	v_mul_f32_e32 v33, 0x4b800000, v32
	v_cmp_gt_f32_e32 vcc, s40, v32
	v_lshlrev_b32_e32 v46, 16, v18
	v_and_b32_e32 v47, 0xffff0000, v18
	v_cndmask_b32_e32 v32, v32, v33, vcc
	v_rsq_f32_e32 v32, v32
	v_lshlrev_b32_e32 v18, 16, v19
	v_and_b32_e32 v19, 0xffff0000, v19
	v_lshlrev_b32_e32 v52, 16, v20
	v_mul_f32_e32 v33, 0x45800000, v32
	v_cndmask_b32_e32 v32, v32, v33, vcc
	v_pk_mul_f32 v[28:29], v[28:29], v[32:33] op_sel_hi:[1,0]
	v_pk_mul_f32 v[30:31], v[30:31], v[32:33] op_sel_hi:[1,0]
	v_pk_mul_f32 v[34:35], v[34:35], v[32:33] op_sel_hi:[1,0]
	v_pk_mul_f32 v[26:27], v[26:27], v[32:33] op_sel_hi:[1,0]
	v_and_b32_e32 v53, 0xffff0000, v20
	v_lshlrev_b32_e32 v20, 16, v21
	v_and_b32_e32 v21, 0xffff0000, v21
	v_pk_fma_f32 v[6:7], v[116:117], v[28:29], v[124:125]
	v_pk_fma_f32 v[8:9], v[118:119], v[30:31], v[126:127]
	v_pk_fma_f32 v[2:3], v[120:121], v[34:35], v[128:129]
	v_pk_fma_f32 v[4:5], v[122:123], v[26:27], v[130:131]
	v_lshlrev_b32_e32 v44, 16, v22
	v_and_b32_e32 v45, 0xffff0000, v22
	v_lshlrev_b32_e32 v22, 16, v23
	v_and_b32_e32 v23, 0xffff0000, v23
	v_lshlrev_b32_e32 v50, 16, v24
	v_and_b32_e32 v51, 0xffff0000, v24
	v_lshlrev_b32_e32 v24, 16, v25
	v_and_b32_e32 v25, 0xffff0000, v25
	v_pk_fma_f32 v[6:7], v[0:1], v[46:47], v[6:7] op_sel_hi:[0,1,1]
	v_pk_fma_f32 v[8:9], v[0:1], v[18:19], v[8:9] op_sel_hi:[0,1,1]
	v_pk_fma_f32 v[2:3], v[0:1], v[52:53], v[2:3] op_sel_hi:[0,1,1]
	v_pk_fma_f32 v[4:5], v[0:1], v[20:21], v[4:5] op_sel_hi:[0,1,1]
	v_pk_mul_f32 v[6:7], v[6:7], v[44:45]
	v_pk_mul_f32 v[8:9], v[8:9], v[22:23]
	v_pk_mul_f32 v[10:11], v[2:3], v[50:51]
	v_pk_mul_f32 v[12:13], v[4:5], v[24:25]
	v_cvt_pk_bf16_f32 v2, v6, v7
	v_cvt_pk_bf16_f32 v3, v8, v9
	v_cvt_pk_bf16_f32 v4, v10, v11
	v_cvt_pk_bf16_f32 v5, v12, v13
	flat_store_dwordx4 v[38:39], v[2:5] offset:1024
	v_lshlrev_b32_e32 v102, 16, v90
	v_and_b32_e32 v103, 0xffff0000, v90
	v_pk_add_f32 v[94:95], v[94:95], v[96:97]
	v_lshlrev_b32_e32 v90, 16, v91
	v_pk_add_f32 v[86:87], v[94:95], v[86:87]
	v_and_b32_e32 v91, 0xffff0000, v91
	v_pk_add_f32 v[86:87], v[88:89], v[86:87]
	v_lshlrev_b32_e32 v108, 16, v92
	v_pk_mul_f32 v[86:87], v[86:87], s[22:23] op_sel_hi:[1,0]
	v_and_b32_e32 v109, 0xffff0000, v92
	v_lshlrev_b32_e32 v92, 16, v93
	v_and_b32_e32 v93, 0xffff0000, v93
	v_fma_f32 v96, -v86, v86, v87
	v_pk_add_f32 v[88:89], v[102:103], v[86:87] op_sel_hi:[1,0] neg_lo:[0,1] neg_hi:[0,1]
	v_pk_add_f32 v[90:91], v[90:91], v[86:87] op_sel_hi:[1,0] neg_lo:[0,1] neg_hi:[0,1]
	v_pk_add_f32 v[94:95], v[108:109], v[86:87] op_sel_hi:[1,0] neg_lo:[0,1] neg_hi:[0,1]
	v_pk_add_f32 v[86:87], v[92:93], v[86:87] op_sel_hi:[1,0] neg_lo:[0,1] neg_hi:[0,1]
	v_max_f32_e32 v92, 0, v96
	v_add_f32_e32 v92, 0x3a27c5ac, v92
	v_mul_f32_e32 v93, 0x4b800000, v92
	v_cmp_gt_f32_e32 vcc, s40, v92
	v_lshlrev_b32_e32 v106, 16, v78
	v_and_b32_e32 v107, 0xffff0000, v78
	v_cndmask_b32_e32 v92, v92, v93, vcc
	v_rsq_f32_e32 v92, v92
	v_lshlrev_b32_e32 v78, 16, v79
	v_and_b32_e32 v79, 0xffff0000, v79
	v_lshlrev_b32_e32 v112, 16, v80
	v_mul_f32_e32 v93, 0x45800000, v92
	v_cndmask_b32_e32 v92, v92, v93, vcc
	v_pk_mul_f32 v[88:89], v[88:89], v[92:93] op_sel_hi:[1,0]
	v_pk_mul_f32 v[90:91], v[90:91], v[92:93] op_sel_hi:[1,0]
	v_pk_mul_f32 v[94:95], v[94:95], v[92:93] op_sel_hi:[1,0]
	v_pk_mul_f32 v[86:87], v[86:87], v[92:93] op_sel_hi:[1,0]
	v_and_b32_e32 v113, 0xffff0000, v80
	v_lshlrev_b32_e32 v80, 16, v81
	v_and_b32_e32 v81, 0xffff0000, v81
	v_pk_fma_f32 v[66:67], v[116:117], v[88:89], v[124:125]
	v_pk_fma_f32 v[68:69], v[118:119], v[90:91], v[126:127]
	v_pk_fma_f32 v[62:63], v[120:121], v[94:95], v[128:129]
	v_pk_fma_f32 v[64:65], v[122:123], v[86:87], v[130:131]
	v_lshlrev_b32_e32 v104, 16, v82
	v_and_b32_e32 v105, 0xffff0000, v82
	v_lshlrev_b32_e32 v82, 16, v83
	v_and_b32_e32 v83, 0xffff0000, v83
	v_lshlrev_b32_e32 v110, 16, v84
	v_and_b32_e32 v111, 0xffff0000, v84
	v_lshlrev_b32_e32 v84, 16, v85
	v_and_b32_e32 v85, 0xffff0000, v85
	v_pk_fma_f32 v[66:67], v[60:61], v[106:107], v[66:67] op_sel_hi:[0,1,1]
	v_pk_fma_f32 v[68:69], v[60:61], v[78:79], v[68:69] op_sel_hi:[0,1,1]
	v_pk_fma_f32 v[62:63], v[60:61], v[112:113], v[62:63] op_sel_hi:[0,1,1]
	v_pk_fma_f32 v[64:65], v[60:61], v[80:81], v[64:65] op_sel_hi:[0,1,1]
	v_pk_mul_f32 v[66:67], v[66:67], v[104:105]
	v_pk_mul_f32 v[68:69], v[68:69], v[82:83]
	v_pk_mul_f32 v[70:71], v[62:63], v[110:111]
	v_pk_mul_f32 v[72:73], v[64:65], v[84:85]
	v_cvt_pk_bf16_f32 v62, v66, v67
	v_cvt_pk_bf16_f32 v63, v68, v69
	v_cvt_pk_bf16_f32 v64, v70, v71
	v_cvt_pk_bf16_f32 v65, v72, v73
	flat_store_dwordx4 v[98:99], v[62:65] offset:1024
	s_andn2_b64 exec, exec, s[20:21]
	s_cbranch_execnz .LBB0_965
